# v14 + S5 pass-2 loop latch: counted vmcnt(2) (the next u tile is older than the step's two y stores) instead of vmcnt(0)
# baseline (speedup 1.0000x reference)
.Ls5w_a:
	v_mov_b64_e32 v[122:123], v[118:119]
	s_cmpk_lg_i32 s36, 0x100
	v_mov_b64_e32 v[120:121], v[116:117]
	s_cbranch_scc0 .LBB0_516

.LBB0_527:
	s_or_b64 exec, exec, s[34:35]
	s_waitcnt lgkmcnt(0)
	s_and_saveexec_b64 s[34:35], s[20:21]
	s_cbranch_execz .LBB0_522
	s_nop 6
	ds_read_b128 v[0:3], v224 offset:256
	ds_read_b128 v[4:7], v224 offset:272
	v_add_u32_e32 v8, s36, v141
	v_ashrrev_i32_e32 v9, 31, v8
	v_lshlrev_b64 v[8:9], 11, v[8:9]
	v_lshl_add_u64 v[8:9], v[146:147], 0, v[8:9]
	s_waitcnt lgkmcnt(1)
	global_store_dwordx4 v[8:9], v[0:3], off nt
	s_waitcnt lgkmcnt(0)
	global_store_dwordx4 v[8:9], v[4:7], off offset:16 nt
	s_or_b64 exec, exec, s[34:35]
	s_waitcnt lgkmcnt(0)
	s_add_i32 s36, s36, 32
	s_waitcnt vmcnt(2)
	s_branch .Ls5w_a

.LBB0_806:
	s_or_b64 exec, exec, s[34:35]
	s_waitcnt lgkmcnt(0)
	s_and_saveexec_b64 s[34:35], s[20:21]
	s_cbranch_execz .LBB0_801
	s_nop 6
	ds_read_b128 v[0:3], v221 offset:256
	ds_read_b128 v[4:7], v221 offset:272
	v_add_u32_e32 v8, s36, v133
	v_ashrrev_i32_e32 v9, 31, v8
	v_lshlrev_b64 v[8:9], 11, v[8:9]
	v_lshl_add_u64 v[8:9], v[144:145], 0, v[8:9]
	s_waitcnt lgkmcnt(1)
	global_store_dwordx4 v[8:9], v[0:3], off nt
	s_waitcnt lgkmcnt(0)
	global_store_dwordx4 v[8:9], v[4:7], off offset:16 nt
	s_or_b64 exec, exec, s[34:35]
	s_waitcnt lgkmcnt(0)
	s_add_i32 s36, s36, 32
	s_waitcnt vmcnt(2)
	s_branch .Ls5w_b
